# k35 + nt on P4a q|k|v stores
# baseline (speedup 1.0000x reference)
.Lalb_3:
	s_waitcnt vmcnt(0)
	v_pk_mul_f32 v[126:127], v[168:169], s[38:39] op_sel_hi:[1,0]
	v_pk_mul_f32 v[156:157], v[160:161], s[38:39] op_sel_hi:[1,0]
	v_pk_mul_f32 v[160:161], v[158:159], s[38:39] op_sel_hi:[1,0]
	v_pk_mul_f32 v[158:159], v[166:167], s[38:39] op_sel_hi:[1,0]
	v_mul_f32_e32 v166, v160, v153
	v_mul_f32_e32 v167, v161, v153
	v_mul_f32_e32 v168, v156, v153
	v_mul_f32_e32 v169, v157, v153
	v_mul_f32_e32 v171, v153, v158
	v_mul_f32_e32 v180, v153, v159
	v_mul_f32_e32 v181, v153, v126
	v_mul_f32_e32 v153, v153, v127
	v_mul_f32_e32 v166, v166, v172
	v_mul_f32_e32 v167, v167, v173
	v_mul_f32_e32 v168, v168, v174
	v_mul_f32_e32 v169, v169, v175
	v_mul_f32_e32 v171, v171, v176
	v_mul_f32_e32 v172, v180, v177
	v_mul_f32_e32 v173, v181, v178
	v_mul_f32_e32 v153, v153, v179
	v_cvt_pk_bf16_f32 v166, v166, v167
	v_cvt_pk_bf16_f32 v167, v168, v169
	v_cvt_pk_bf16_f32 v168, v171, v172
	v_cvt_pk_bf16_f32 v169, v173, v153
	global_store_dwordx4 v[224:225], v[166:169], off nt
	s_nop 1
	v_cvt_f32_i32_e32 v171, v116
	v_cvt_f32_i32_e32 v168, v114
	v_cvt_f32_i32_e32 v169, v115
	v_cvt_f32_i32_e32 v172, v117
	v_or_b32_e32 v166, 32, v152
	v_ashrrev_i32_e32 v167, 31, v166
	s_nop 0
	v_lshl_add_u64 v[116:117], v[166:167], 2, s[26:27]
	s_nop 0
	v_cvt_f32_i32_e32 v41, v41
	v_cvt_f32_i32_e32 v34, v34
	v_cvt_f32_i32_e32 v35, v35
	v_cvt_f32_i32_e32 v36, v36
	v_cvt_f32_i32_e32 v29, v29
	v_cvt_f32_i32_e32 v30, v30
	v_cvt_f32_i32_e32 v31, v31
	v_cvt_f32_i32_e32 v32, v32
	v_cvt_f32_i32_e32 v33, v33
	v_cvt_f32_i32_e32 v26, v26
	v_cvt_f32_i32_e32 v27, v27
	v_cvt_f32_i32_e32 v28, v28
	v_cvt_f32_i32_e32 v21, v21
	v_cvt_f32_i32_e32 v22, v22
	v_cvt_f32_i32_e32 v23, v23
	v_cvt_f32_i32_e32 v24, v24
	v_cvt_f32_i32_e32 v25, v25
	v_cvt_f32_i32_e32 v18, v18
	v_cvt_f32_i32_e32 v19, v19
	v_cvt_f32_i32_e32 v20, v20
	v_cvt_f32_i32_e32 v13, v13
	v_cvt_f32_i32_e32 v14, v14
	v_cvt_f32_i32_e32 v15, v15
	v_cvt_f32_i32_e32 v16, v16
	v_cvt_f32_i32_e32 v17, v17
	v_cvt_f32_i32_e32 v10, v10
	v_cvt_f32_i32_e32 v11, v11
	v_cvt_f32_i32_e32 v12, v12
	v_cvt_f32_i32_e32 v5, v5
	v_cvt_f32_i32_e32 v6, v6
	v_cvt_f32_i32_e32 v7, v7
	v_cvt_f32_i32_e32 v8, v8
	v_cvt_f32_i32_e32 v9, v9
	v_cvt_f32_i32_e32 v2, v2
	v_cvt_f32_i32_e32 v3, v3
	v_cvt_f32_i32_e32 v4, v4
	s_and_b64 vcc, exec, s[4:5]
	v_mov_b32_e32 v153, v192
	v_mul_f32_e32 v167, v160, v153
	v_mul_f32_e32 v170, v161, v153
	v_mul_f32_e32 v173, v156, v153
	v_mul_f32_e32 v174, v157, v153
	v_mul_f32_e32 v175, v158, v153
	v_mul_f32_e32 v176, v159, v153
	v_mul_f32_e32 v177, v126, v153
	v_mul_f32_e32 v153, v127, v153
	v_mul_f32_e32 v118, v167, v118
	v_mul_f32_e32 v119, v170, v119
	v_mul_f32_e32 v120, v173, v120
	v_mul_f32_e32 v121, v174, v121
	v_mul_f32_e32 v167, v175, v168
	v_mul_f32_e32 v168, v176, v169
	v_mul_f32_e32 v169, v177, v171
	v_mul_f32_e32 v153, v153, v172
	v_cvt_pk_bf16_f32 v118, v118, v119
	v_cvt_pk_bf16_f32 v119, v120, v121
	v_cvt_pk_bf16_f32 v120, v167, v168
	v_cvt_pk_bf16_f32 v121, v169, v153
	global_store_dwordx4 v[228:229], v[118:121], off nt
	s_nop 1
	v_cvt_f32_i32_e32 v153, v107
	v_cvt_f32_i32_e32 v121, v106
	v_cvt_f32_i32_e32 v167, v108
	v_cvt_f32_i32_e32 v168, v109
	v_or_b32_e32 v118, 48, v152
	v_ashrrev_i32_e32 v119, 31, v118
	s_nop 0
	v_lshl_add_u64 v[108:109], v[118:119], 2, s[26:27]
	s_nop 0
	v_mov_b32_e32 v120, v194
	v_mul_f32_e32 v119, v160, v120
	v_mul_f32_e32 v166, v161, v120
	v_mul_f32_e32 v169, v156, v120
	v_mul_f32_e32 v170, v157, v120
	v_mul_f32_e32 v171, v158, v120
	v_mul_f32_e32 v172, v159, v120
	v_mul_f32_e32 v173, v126, v120
	v_mul_f32_e32 v120, v127, v120
	v_mul_f32_e32 v110, v119, v110
	v_mul_f32_e32 v111, v166, v111
	v_mul_f32_e32 v112, v169, v112
	v_mul_f32_e32 v113, v170, v113
	v_mul_f32_e32 v119, v171, v121
	v_mul_f32_e32 v121, v172, v153
	v_mul_f32_e32 v153, v173, v167
	v_mul_f32_e32 v120, v120, v168
	v_cvt_pk_bf16_f32 v110, v110, v111
	v_cvt_pk_bf16_f32 v111, v112, v113
	v_cvt_pk_bf16_f32 v112, v119, v121
	v_cvt_pk_bf16_f32 v113, v153, v120
	global_store_dwordx4 v[232:233], v[110:113], off nt
	s_nop 1
	v_mov_b32_e32 v110, v196
	v_mul_f32_e32 v119, v156, v110
	v_cvt_f32_i32_e32 v111, v98
	v_cvt_f32_i32_e32 v112, v99
	s_nop 0
	v_mul_f32_e32 v113, v160, v110
	v_mul_f32_e32 v118, v161, v110
	s_nop 0
	v_mul_f32_e32 v120, v157, v110
	v_mul_f32_e32 v121, v158, v110
	v_mul_f32_e32 v153, v159, v110
	v_mul_f32_e32 v166, v126, v110
	v_mul_f32_e32 v110, v127, v110
	v_mul_f32_e32 v102, v113, v102
	v_mul_f32_e32 v103, v118, v103
	v_mul_f32_e32 v104, v119, v104
	v_mul_f32_e32 v105, v120, v105
	v_mul_f32_e32 v111, v121, v111
	v_mul_f32_e32 v112, v153, v112
	v_mul_f32_e32 v113, v166, v100
	v_mul_f32_e32 v110, v110, v101
	v_cvt_pk_bf16_f32 v100, v102, v103
	v_cvt_pk_bf16_f32 v101, v104, v105
	v_cvt_pk_bf16_f32 v102, v111, v112
	v_cvt_pk_bf16_f32 v103, v113, v110
	global_store_dwordx4 v[236:237], v[100:103], off nt
	s_nop 1
	v_mov_b32_e32 v100, v198
	v_mul_f32_e32 v104, v161, v100
	v_cvt_f32_i32_e32 v101, v90
	v_cvt_f32_i32_e32 v102, v91
	v_add_u32_e32 v90, 0x80, v152
	s_nop 0
	v_mul_f32_e32 v103, v160, v100
	s_nop 0
	v_mul_f32_e32 v105, v156, v100
	v_mul_f32_e32 v110, v157, v100
	v_mul_f32_e32 v111, v158, v100
	v_mul_f32_e32 v112, v159, v100
	v_mul_f32_e32 v113, v126, v100
	v_mul_f32_e32 v100, v127, v100
	v_mul_f32_e32 v94, v103, v94
	v_mul_f32_e32 v95, v104, v95
	v_mul_f32_e32 v96, v105, v96
	v_mul_f32_e32 v97, v110, v97
	v_mul_f32_e32 v101, v111, v101
	v_mul_f32_e32 v102, v112, v102
	v_mul_f32_e32 v103, v113, v92
	v_mul_f32_e32 v100, v100, v93
	v_cvt_pk_bf16_f32 v92, v94, v95
	v_cvt_pk_bf16_f32 v93, v96, v97
	v_cvt_pk_bf16_f32 v94, v101, v102
	v_cvt_pk_bf16_f32 v95, v103, v100
	global_store_dwordx4 v[240:241], v[92:95], off nt
	s_nop 1
	v_mov_b32_e32 v92, v200
	v_mul_f32_e32 v96, v161, v92
	v_cvt_f32_i32_e32 v93, v82
	v_cvt_f32_i32_e32 v94, v83
	v_add_u32_e32 v82, 0x90, v152
	s_nop 0
	v_mul_f32_e32 v95, v160, v92
	s_nop 0
	v_mul_f32_e32 v97, v156, v92
	v_mul_f32_e32 v100, v157, v92
	v_mul_f32_e32 v101, v158, v92
	v_mul_f32_e32 v102, v159, v92
	v_mul_f32_e32 v103, v126, v92
	v_mul_f32_e32 v92, v127, v92
	v_mul_f32_e32 v86, v95, v86
	v_mul_f32_e32 v87, v96, v87
	v_mul_f32_e32 v88, v97, v88
	v_mul_f32_e32 v89, v100, v89
	v_mul_f32_e32 v93, v101, v93
	v_mul_f32_e32 v94, v102, v94
	v_mul_f32_e32 v95, v103, v84
	v_mul_f32_e32 v92, v92, v85
	v_cvt_pk_bf16_f32 v84, v86, v87
	v_cvt_pk_bf16_f32 v85, v88, v89
	v_cvt_pk_bf16_f32 v86, v93, v94
	v_cvt_pk_bf16_f32 v87, v95, v92
	global_store_dwordx4 v[244:245], v[84:87], off nt
	s_nop 1
	v_mov_b32_e32 v84, v202
	v_mul_f32_e32 v88, v161, v84
	v_cvt_f32_i32_e32 v85, v74
	v_cvt_f32_i32_e32 v86, v75
	v_add_u32_e32 v74, 0xa0, v152
	s_nop 0
	v_mul_f32_e32 v87, v160, v84
	s_nop 0
	v_mul_f32_e32 v89, v156, v84
	v_mul_f32_e32 v92, v157, v84
	v_mul_f32_e32 v93, v158, v84
	v_mul_f32_e32 v94, v159, v84
	v_mul_f32_e32 v95, v126, v84
	v_mul_f32_e32 v84, v127, v84
	v_mul_f32_e32 v78, v87, v78
	v_mul_f32_e32 v79, v88, v79
	v_mul_f32_e32 v80, v89, v80
	v_mul_f32_e32 v81, v92, v81
	v_mul_f32_e32 v85, v93, v85
	v_mul_f32_e32 v86, v94, v86
	v_mul_f32_e32 v87, v95, v76
	v_mul_f32_e32 v84, v84, v77
	v_cvt_pk_bf16_f32 v76, v78, v79
	v_cvt_pk_bf16_f32 v77, v80, v81
	v_cvt_pk_bf16_f32 v78, v85, v86
	v_cvt_pk_bf16_f32 v79, v87, v84
	global_store_dwordx4 v[248:249], v[76:79], off nt
	s_nop 1
	v_cvt_f32_i32_e32 v88, v61
	v_cvt_f32_i32_e32 v77, v62
	v_cvt_f32_i32_e32 v78, v63
	v_add_u32_e32 v62, 0xb0, v152
	s_nop 0
	s_nop 0
	s_mov_b64 s[0:1], -1
	v_mov_b32_e32 v76, v204
	v_mul_f32_e32 v79, v160, v76
	v_mul_f32_e32 v80, v161, v76
	v_mul_f32_e32 v81, v156, v76
	v_mul_f32_e32 v84, v157, v76
	v_mul_f32_e32 v85, v158, v76
	v_mul_f32_e32 v86, v159, v76
	v_mul_f32_e32 v87, v126, v76
	v_mul_f32_e32 v76, v127, v76
	v_mul_f32_e32 v70, v79, v70
	v_mul_f32_e32 v71, v80, v71
	v_mul_f32_e32 v72, v81, v72
	v_mul_f32_e32 v73, v84, v73
	v_mul_f32_e32 v77, v85, v77
	v_mul_f32_e32 v78, v86, v78
	v_mul_f32_e32 v64, v87, v64
	v_mul_f32_e32 v65, v76, v65
	v_cvt_pk_bf16_f32 v70, v70, v71
	v_cvt_pk_bf16_f32 v71, v72, v73
	v_cvt_pk_bf16_f32 v72, v77, v78
	v_cvt_pk_bf16_f32 v73, v64, v65
	global_store_dwordx4 v[252:253], v[70:73], off nt
	s_nop 1
	s_nop 1
	v_cvt_f32_i32_e32 v81, v66
	v_cvt_f32_i32_e32 v84, v67
	v_cvt_f32_i32_e32 v85, v58
	v_cvt_f32_i32_e32 v86, v59
	v_cvt_f32_i32_e32 v87, v60
	v_pk_mul_f32 v[60:61], v[208:209], s[38:39] op_sel_hi:[1,0]
	v_pk_mul_f32 v[66:67], v[206:207], s[38:39] op_sel_hi:[1,0]
	v_pk_mul_f32 v[58:59], v[212:213], s[38:39] op_sel_hi:[1,0]
	v_pk_mul_f32 v[64:65], v[210:211], s[38:39] op_sel_hi:[1,0]
	v_mov_b32_e32 v80, v190
	v_mul_f32_e32 v70, v66, v80
	v_mul_f32_e32 v71, v67, v80
	v_mul_f32_e32 v73, v61, v80
	v_mul_f32_e32 v72, v60, v80
	v_mul_f32_e32 v76, v80, v64
	v_mul_f32_e32 v77, v80, v65
	v_mul_f32_e32 v78, v80, v58
	v_mul_f32_e32 v79, v80, v59
	v_mul_f32_e32 v70, v70, v81
	v_mul_f32_e32 v71, v71, v84
	v_mul_f32_e32 v69, v73, v69
	v_mul_f32_e32 v72, v72, v68
	v_mul_f32_e32 v73, v76, v85
	v_mul_f32_e32 v76, v77, v86
	v_mul_f32_e32 v77, v78, v87
	v_mul_f32_e32 v78, v79, v88
	v_cvt_pk_bf16_f32 v68, v70, v71
	v_cvt_pk_bf16_f32 v69, v72, v69
	v_cvt_pk_bf16_f32 v70, v73, v76
	v_cvt_pk_bf16_f32 v71, v77, v78
	global_store_dwordx4 v[226:227], v[68:71], off nt
	s_nop 1
	v_mov_b32_e32 v68, v192
	v_mul_f32_e32 v72, v61, v68
	v_mul_f32_e32 v69, v66, v68
	v_mul_f32_e32 v70, v67, v68
	v_mul_f32_e32 v71, v60, v68
	v_mul_f32_e32 v73, v64, v68
	v_mul_f32_e32 v76, v65, v68
	v_mul_f32_e32 v77, v58, v68
	v_mul_f32_e32 v68, v59, v68
	v_mul_f32_e32 v53, v68, v53
	v_mul_f32_e32 v54, v69, v54
	v_mul_f32_e32 v55, v70, v55
	v_mul_f32_e32 v56, v71, v56
	v_mul_f32_e32 v57, v72, v57
	v_mul_f32_e32 v69, v73, v50
	v_mul_f32_e32 v70, v76, v51
	v_mul_f32_e32 v71, v77, v52
	v_cvt_pk_bf16_f32 v50, v54, v55
	v_cvt_pk_bf16_f32 v51, v56, v57
	v_cvt_pk_bf16_f32 v52, v69, v70
	v_cvt_pk_bf16_f32 v53, v71, v53
	global_store_dwordx4 v[230:231], v[50:53], off nt
	s_nop 1
	v_mov_b32_e32 v50, v194
	v_mul_f32_e32 v54, v61, v50
	v_mul_f32_e32 v51, v66, v50
	v_mul_f32_e32 v52, v67, v50
	v_mul_f32_e32 v53, v60, v50
	v_mul_f32_e32 v55, v64, v50
	v_mul_f32_e32 v56, v65, v50
	v_mul_f32_e32 v57, v58, v50
	v_mul_f32_e32 v50, v59, v50
	v_mul_f32_e32 v45, v50, v45
	v_mul_f32_e32 v46, v51, v46
	v_mul_f32_e32 v47, v52, v47
	v_mul_f32_e32 v48, v53, v48
	v_mul_f32_e32 v49, v54, v49
	v_mul_f32_e32 v51, v55, v42
	v_mul_f32_e32 v52, v56, v43
	v_mul_f32_e32 v53, v57, v44
	v_cvt_pk_bf16_f32 v42, v46, v47
	v_cvt_pk_bf16_f32 v43, v48, v49
	v_cvt_pk_bf16_f32 v44, v51, v52
	v_cvt_pk_bf16_f32 v45, v53, v45
	global_store_dwordx4 v[234:235], v[42:45], off nt
	s_nop 1
	v_mov_b32_e32 v42, v196
	v_mul_f32_e32 v46, v61, v42
	v_mul_f32_e32 v43, v66, v42
	v_mul_f32_e32 v44, v67, v42
	v_mul_f32_e32 v45, v60, v42
	v_mul_f32_e32 v47, v64, v42
	v_mul_f32_e32 v48, v65, v42
	v_mul_f32_e32 v49, v58, v42
	v_mul_f32_e32 v42, v59, v42
	v_mul_f32_e32 v37, v42, v37
	v_mul_f32_e32 v38, v43, v38
	v_mul_f32_e32 v39, v44, v39
	v_mul_f32_e32 v40, v45, v40
	v_mul_f32_e32 v41, v46, v41
	v_mul_f32_e32 v43, v47, v34
	v_mul_f32_e32 v44, v48, v35
	v_mul_f32_e32 v45, v49, v36
	v_cvt_pk_bf16_f32 v34, v38, v39
	v_cvt_pk_bf16_f32 v35, v40, v41
	v_cvt_pk_bf16_f32 v36, v43, v44
	v_cvt_pk_bf16_f32 v37, v45, v37
	global_store_dwordx4 v[238:239], v[34:37], off nt
	s_nop 1
	v_mov_b32_e32 v34, v198
	v_mul_f32_e32 v38, v61, v34
	v_mul_f32_e32 v35, v66, v34
	v_mul_f32_e32 v36, v67, v34
	v_mul_f32_e32 v37, v60, v34
	v_mul_f32_e32 v39, v64, v34
	v_mul_f32_e32 v40, v65, v34
	v_mul_f32_e32 v41, v58, v34
	v_mul_f32_e32 v34, v59, v34
	v_mul_f32_e32 v29, v34, v29
	v_mul_f32_e32 v30, v35, v30
	v_mul_f32_e32 v31, v36, v31
	v_mul_f32_e32 v32, v37, v32
	v_mul_f32_e32 v33, v38, v33
	v_mul_f32_e32 v35, v39, v26
	v_mul_f32_e32 v36, v40, v27
	v_mul_f32_e32 v37, v41, v28
	v_cvt_pk_bf16_f32 v26, v30, v31
	v_cvt_pk_bf16_f32 v27, v32, v33
	v_cvt_pk_bf16_f32 v28, v35, v36
	v_cvt_pk_bf16_f32 v29, v37, v29
	global_store_dwordx4 v[242:243], v[26:29], off nt
	s_nop 1
	v_mov_b32_e32 v26, v200
	v_mul_f32_e32 v30, v61, v26
	v_mul_f32_e32 v27, v66, v26
	v_mul_f32_e32 v28, v67, v26
	v_mul_f32_e32 v29, v60, v26
	v_mul_f32_e32 v31, v64, v26
	v_mul_f32_e32 v32, v65, v26
	v_mul_f32_e32 v33, v58, v26
	v_mul_f32_e32 v26, v59, v26
	v_mul_f32_e32 v21, v26, v21
	v_mul_f32_e32 v22, v27, v22
	v_mul_f32_e32 v23, v28, v23
	v_mul_f32_e32 v24, v29, v24
	v_mul_f32_e32 v25, v30, v25
	v_mul_f32_e32 v27, v31, v18
	v_mul_f32_e32 v28, v32, v19
	v_mul_f32_e32 v29, v33, v20
	v_cvt_pk_bf16_f32 v18, v22, v23
	v_cvt_pk_bf16_f32 v19, v24, v25
	v_cvt_pk_bf16_f32 v20, v27, v28
	v_cvt_pk_bf16_f32 v21, v29, v21
	global_store_dwordx4 v[246:247], v[18:21], off nt
	s_nop 1
	v_mov_b32_e32 v18, v202
	v_mul_f32_e32 v22, v61, v18
	v_mul_f32_e32 v19, v66, v18
	v_mul_f32_e32 v20, v67, v18
	v_mul_f32_e32 v21, v60, v18
	v_mul_f32_e32 v23, v64, v18
	v_mul_f32_e32 v24, v65, v18
	v_mul_f32_e32 v25, v58, v18
	v_mul_f32_e32 v18, v59, v18
	v_mul_f32_e32 v13, v18, v13
	v_mul_f32_e32 v14, v19, v14
	v_mul_f32_e32 v15, v20, v15
	v_mul_f32_e32 v16, v21, v16
	v_mul_f32_e32 v17, v22, v17
	v_mul_f32_e32 v19, v23, v10
	v_mul_f32_e32 v20, v24, v11
	v_mul_f32_e32 v21, v25, v12
	v_cvt_pk_bf16_f32 v10, v14, v15
	v_cvt_pk_bf16_f32 v11, v16, v17
	v_cvt_pk_bf16_f32 v12, v19, v20
	v_cvt_pk_bf16_f32 v13, v21, v13
	global_store_dwordx4 v[250:251], v[10:13], off nt
	s_nop 1
	v_mov_b32_e32 v10, v204
	v_mul_f32_e32 v14, v61, v10
	v_mul_f32_e32 v11, v66, v10
	v_mul_f32_e32 v12, v67, v10
	v_mul_f32_e32 v13, v60, v10
	v_mul_f32_e32 v15, v64, v10
	v_mul_f32_e32 v16, v65, v10
	v_mul_f32_e32 v17, v58, v10
	v_mul_f32_e32 v10, v59, v10
	v_mul_f32_e32 v5, v10, v5
	v_mul_f32_e32 v6, v11, v6
	v_mul_f32_e32 v7, v12, v7
	v_mul_f32_e32 v8, v13, v8
	v_mul_f32_e32 v9, v14, v9
	v_mul_f32_e32 v11, v15, v2
	v_mul_f32_e32 v12, v16, v3
	v_mul_f32_e32 v13, v17, v4
	v_cvt_pk_bf16_f32 v2, v6, v7
	v_cvt_pk_bf16_f32 v3, v8, v9
	v_cvt_pk_bf16_f32 v4, v11, v12
	v_cvt_pk_bf16_f32 v5, v13, v5
	global_store_dwordx4 v[254:255], v[2:5], off nt
	s_cbranch_vccnz .LBB0_552
	s_andn2_b64 vcc, exec, s[16:17]
	s_cbranch_vccnz .LBB0_551
	s_barrier
	s_branch .LBB0_551
